# DIFF flash loop: fast-path exp block runs at s_setprio 2, then back to the wave's static priority (transcendental section prioritized over the co-resident wave)
# speedup vs baseline: 1.0046x; 1.0007x over previous
.LBB0_494:
	s_andn2_saveexec_b64 s[0:1], s[0:1]
	s_cbranch_execz .LBB0_496
	s_setprio 2
	v_sub_f32_e32 v33, v201, v247
	v_fmamk_f32 v2, v114, 0x3e38aa3b, v33
	v_exp_f32_e32 v2, v2
	v_fmamk_f32 v3, v115, 0x3e38aa3b, v33
	v_exp_f32_e32 v3, v3
	v_fmamk_f32 v4, v116, 0x3e38aa3b, v33
	v_exp_f32_e32 v4, v4
	v_add_f32_e32 v5, 0, v2
	v_add_f32_e32 v5, v3, v5
	v_fmamk_f32 v6, v118, 0x3e38aa3b, v33
	v_add_f32_e32 v9, v4, v5
	v_fmamk_f32 v5, v117, 0x3e38aa3b, v33
	v_exp_f32_e32 v5, v5
	v_exp_f32_e32 v6, v6
	v_fmamk_f32 v7, v119, 0x3e38aa3b, v33
	v_exp_f32_e32 v7, v7
	v_fmamk_f32 v8, v120, 0x3e38aa3b, v33
	v_exp_f32_e32 v8, v8
	v_add_f32_e32 v9, v5, v9
	v_add_f32_e32 v9, v6, v9
	v_add_f32_e32 v9, v7, v9
	v_add_f32_e32 v13, v8, v9
	v_fmamk_f32 v9, v121, 0x3e38aa3b, v33
	v_exp_f32_e32 v9, v9
	v_fmamk_f32 v10, v122, 0x3e38aa3b, v33
	v_exp_f32_e32 v10, v10
	v_fmamk_f32 v11, v123, 0x3e38aa3b, v33
	v_exp_f32_e32 v11, v11
	v_fmamk_f32 v12, v124, 0x3e38aa3b, v33
	v_exp_f32_e32 v12, v12
	v_add_f32_e32 v13, v9, v13
	v_add_f32_e32 v13, v10, v13
	v_add_f32_e32 v13, v11, v13
	v_add_f32_e32 v17, v12, v13
	v_fmamk_f32 v13, v125, 0x3e38aa3b, v33
	v_exp_f32_e32 v13, v13
	v_fmamk_f32 v14, v126, 0x3e38aa3b, v33
	v_exp_f32_e32 v14, v14
	v_fmamk_f32 v15, v127, 0x3e38aa3b, v33
	v_exp_f32_e32 v15, v15
	v_fmamk_f32 v16, v128, 0x3e38aa3b, v33
	v_exp_f32_e32 v16, v16
	v_add_f32_e32 v17, v13, v17
	v_add_f32_e32 v17, v14, v17
	v_add_f32_e32 v17, v15, v17
	v_add_f32_e32 v21, v16, v17
	v_fmamk_f32 v17, v129, 0x3e38aa3b, v33
	v_exp_f32_e32 v17, v17
	v_fmamk_f32 v18, v98, 0x3e38aa3b, v33
	v_exp_f32_e32 v18, v18
	v_fmamk_f32 v19, v99, 0x3e38aa3b, v33
	v_exp_f32_e32 v19, v19
	v_fmamk_f32 v20, v100, 0x3e38aa3b, v33
	v_exp_f32_e32 v20, v20
	v_add_f32_e32 v21, v17, v21
	v_add_f32_e32 v21, v18, v21
	v_add_f32_e32 v21, v19, v21
	v_add_f32_e32 v25, v20, v21
	v_fmamk_f32 v21, v101, 0x3e38aa3b, v33
	v_exp_f32_e32 v21, v21
	v_fmamk_f32 v22, v102, 0x3e38aa3b, v33
	v_exp_f32_e32 v22, v22
	v_fmamk_f32 v23, v103, 0x3e38aa3b, v33
	v_exp_f32_e32 v23, v23
	v_fmamk_f32 v24, v104, 0x3e38aa3b, v33
	v_exp_f32_e32 v24, v24
	v_add_f32_e32 v25, v21, v25
	v_add_f32_e32 v25, v22, v25
	v_add_f32_e32 v25, v23, v25
	v_add_f32_e32 v29, v24, v25
	v_fmamk_f32 v25, v105, 0x3e38aa3b, v33
	v_exp_f32_e32 v25, v25
	v_fmamk_f32 v26, v106, 0x3e38aa3b, v33
	v_exp_f32_e32 v26, v26
	v_fmamk_f32 v27, v107, 0x3e38aa3b, v33
	v_exp_f32_e32 v27, v27
	v_fmamk_f32 v28, v108, 0x3e38aa3b, v33
	v_exp_f32_e32 v28, v28
	v_add_f32_e32 v29, v25, v29
	v_add_f32_e32 v29, v26, v29
	v_add_f32_e32 v29, v27, v29
	v_add_f32_e32 v98, v28, v29
	v_fmamk_f32 v29, v109, 0x3e38aa3b, v33
	v_exp_f32_e32 v29, v29
	v_fmamk_f32 v30, v110, 0x3e38aa3b, v33
	v_exp_f32_e32 v30, v30
	v_fmamk_f32 v31, v111, 0x3e38aa3b, v33
	v_exp_f32_e32 v31, v31
	v_fmamk_f32 v32, v112, 0x3e38aa3b, v33
	v_exp_f32_e32 v32, v32
	v_add_f32_e32 v98, v29, v98
	v_add_f32_e32 v98, v30, v98
	v_add_f32_e32 v98, v31, v98
	v_add_f32_e32 v248, v32, v98
	v_fmac_f32_e32 v33, 0x3e38aa3b, v113
	s_getreg_b32 s98, hwreg(HW_REG_HW_ID, 0, 1)
	s_cmp_eq_u32 s98, 1
	s_cbranch_scc1 .Lexp_odd
	s_setprio 0
	s_branch .LBB0_496
.Lexp_odd:
	s_setprio 1
